# A-pair attention loops: QK MFMAs take the running -max tuple / partial accumulator directly as SrcC instead of copying 16 registers first (16 fewer v_mov_b64 per iteration)
# baseline (speedup 1.0000x reference)
.LBB0_654:
	v_add_u32_e32 v200, s10, v223
	v_mov_b32_e32 v96, 0
	v_mov_b32_e32 v124, 0
	v_add_u32_e32 v97, v200, v96
	ds_read_b128 v[114:117], v97
	ds_read_b128 v[132:135], v97 offset:512
	v_add_u32_e32 v96, v221, v96
	ds_read_b128 v[128:131], v96 offset:51200
	v_exp_f32_e32 v125, v176
	v_add_u32_e32 v118, v200, v124
	ds_read_b128 v[136:139], v118 offset:2048
	s_waitcnt lgkmcnt(0)
	v_mfma_f32_32x32x16_bf16 v[96:111], v[114:117], v[128:131], v[144:159]
	ds_read_b128 v[116:119], v118 offset:2560
	v_add_u32_e32 v114, v221, v124
	v_exp_f32_e32 v124, v178
	v_add_f32_e32 v140, v121, v120
	v_add_f32_e32 v141, v123, v122
	v_exp_f32_e32 v201, v166
	v_exp_f32_e32 v211, v167
	v_mfma_f32_32x32x16_bf16 v[144:159], v[132:135], v[128:131], v[144:159]
	v_exp_f32_e32 v133, v177
	v_exp_f32_e32 v129, v160
	v_exp_f32_e32 v131, v161
	v_exp_f32_e32 v132, v179
	v_exp_f32_e32 v128, v162
	v_exp_f32_e32 v130, v163
	ds_read_b128 v[120:123], v114 offset:59392
	v_add_f32_e32 v134, v132, v124
	v_add_f32_e32 v135, v133, v125
	s_waitcnt lgkmcnt(0)
	v_mfma_f32_32x32x16_bf16 v[96:111], v[136:139], v[120:123], v[96:111]
	v_add_f32_e64 v142, v130, v128
	v_add_f32_e64 v143, v131, v129
	v_mov_b32_e32 v136, 0
	v_add_f32_e64 v134, v142, v134
	v_add_f32_e64 v135, v143, v135
	v_cvt_pk_bf16_f32 v114, v125, v133
	v_add_f32_e32 v115, 0, v135
	v_add_f32_e32 v143, v134, v115
	v_cvt_pk_bf16_f32 v115, v124, v132
	v_exp_f32_e32 v133, v180
	v_add_u32_e32 v124, v200, v136
	v_exp_f32_e32 v135, v181
	v_exp_f32_e32 v132, v164
	v_exp_f32_e32 v134, v165
	ds_read_b128 v[160:163], v124 offset:4096
	v_mfma_f32_32x32x16_bf16 v[144:159], v[116:119], v[120:123], v[144:159]
	ds_read_b128 v[122:125], v124 offset:4608
	v_add3_u32 v116, v221, v136, s45
	ds_read_b128 v[176:179], v116
	v_add_f32_e64 v116, v134, v132
	v_add_f32_e64 v117, v135, v133
	v_exp_f32_e32 v118, v182
	v_exp_f32_e32 v119, v183
	v_add_f32_e32 v166, v116, v116
	v_add_f32_e32 v167, v116, v117
	v_exp_f32_e32 v142, v184
	v_exp_f32_e32 v166, v185
	v_exp_f32_e32 v136, v168
	v_exp_f32_e32 v138, v169
	v_mov_b32_e32 v224, 0
	v_exp_f32_e32 v181, v186
	v_exp_f32_e32 v183, v187
	v_exp_f32_e32 v180, v170
	v_exp_f32_e32 v182, v171
	v_cvt_pk_bf16_f32 v116, v133, v135
	v_add_f32_e32 v137, v119, v118
	v_add_f32_e32 v139, v211, v201
	v_cvt_pk_bf16_f32 v117, v118, v119
	v_add_u32_e32 v133, v200, v224
	s_waitcnt lgkmcnt(0)
	v_mfma_f32_32x32x16_bf16 v[96:111], v[160:163], v[176:179], v[96:111]
	ds_read_b128 v[118:121], v133 offset:6144
	v_add_f32_e64 v160, v166, v142
	v_add_f32_e64 v161, v167, v143
	v_add_f32_e64 v162, v138, v136
	v_add_f32_e64 v163, v139, v137
	v_exp_f32_e32 v185, v188
	v_add_f32_e32 v160, v162, v160
	v_add_f32_e32 v161, v163, v161
	v_exp_f32_e32 v187, v189
	v_add_f32_e32 v164, v160, v160
	v_add_f32_e32 v165, v160, v161
	v_mfma_f32_32x32x16_bf16 v[144:159], v[122:125], v[176:179], v[144:159]
	ds_read_b128 v[122:125], v133 offset:6656
	ds_read_b128 v[168:171], v63 offset:8704
	v_cvt_pk_bf16_f32 v160, v142, v166
	v_add_f32_e64 v142, v182, v180
	v_add_f32_e64 v143, v183, v181
	v_exp_f32_e32 v164, v190
	v_add_f32_e32 v166, v142, v142
	v_add_f32_e32 v167, v142, v143
	v_exp_f32_e32 v166, v191
	s_waitcnt lgkmcnt(0)
	v_mfma_f32_32x32x16_bf16 v[32:47], v[114:117], v[168:171], v[32:47]
	ds_read_b128 v[176:179], v63 offset:10752
	v_cvt_pk_bf16_f32 v161, v181, v183
	v_cvt_pk_bf16_f32 v162, v185, v187
	v_cvt_pk_bf16_f32 v163, v164, v166
	v_cvt_pk_bf16_f32 v168, v129, v131
	v_cvt_pk_bf16_f32 v169, v128, v130
	v_cvt_pk_bf16_f32 v170, v132, v134
	s_waitcnt lgkmcnt(0)
	v_mfma_f32_32x32x16_bf16 v[32:47], v[160:163], v[176:179], v[32:47]
	ds_read_b128 v[128:131], v63 offset:12800
	v_cvt_pk_bf16_f32 v171, v201, v211
	v_exp_f32_e32 v181, v172
	v_exp_f32_e32 v183, v173
	v_exp_f32_e32 v184, v174
	v_exp_f32_e32 v186, v175
	v_cvt_pk_bf16_f32 v176, v136, v138
	s_waitcnt lgkmcnt(0)
	v_mfma_f32_32x32x16_bf16 v[32:47], v[168:171], v[128:131], v[32:47]
	ds_read_b128 v[132:135], v63 offset:14848
	v_cvt_pk_bf16_f32 v177, v180, v182
	v_cvt_pk_bf16_f32 v178, v181, v183
	v_cvt_pk_bf16_f32 v179, v184, v186
	v_add_f32_e32 v129, v234, v215
	v_add_f32_e32 v130, v237, v235
	v_add_f32_e32 v129, v130, v129
	v_add3_u32 v130, v221, v224, s18
	s_waitcnt lgkmcnt(0)
	v_mfma_f32_32x32x16_bf16 v[32:47], v[176:179], v[132:135], v[32:47]
	ds_read_b128 v[172:175], v130
	v_add_f32_e32 v128, v141, v140
	v_add_f32_e32 v128, 0, v128
	v_add_f32_e32 v128, v129, v128
	v_add_f32_e32 v113, v213, v113
	v_add_f32_e32 v129, v236, v232
	v_add_f32_e32 v113, v129, v113
	s_waitcnt lgkmcnt(0)
	v_mfma_f32_32x32x16_bf16 v[96:111], v[118:121], v[172:175], v[96:111]
	v_add_f32_e32 v118, v238, v233
	v_add_f32_e32 v119, v240, v239
	v_add_f32_e32 v113, v113, v128
	v_add_f32_e32 v118, v119, v118
	v_add_f32_e32 v113, v118, v113
	ds_read_b128 v[118:121], v63 offset:8192
	v_mfma_f32_32x32x16_bf16 v[128:143], v[122:125], v[172:175], v[144:159]
	v_add_f32_e32 v122, v242, v241
	v_add_f32_e32 v123, v247, v245
	v_add_f32_e32 v122, v123, v122
	v_add_f32_e32 v113, v122, v113
	ds_read_b128 v[122:125], v63 offset:10240
	v_add_f32_e32 v185, v187, v185
	v_add_f32_e32 v187, v183, v181
	s_waitcnt lgkmcnt(0)
	v_mfma_f32_32x32x16_bf16 v[64:79], v[114:117], v[118:121], v[64:79]
	v_add_f32_e32 v144, v250, v249
	v_add_f32_e32 v145, v228, v227
	v_add_f32_e32 v114, v145, v144
	v_add_f32_e32 v113, v114, v113
	v_add_f32_e32 v114, v248, v246
	v_add_f32_e32 v115, v226, v225
	v_add_f32_e32 v114, v115, v114
	v_add_f32_e32 v113, v114, v113
	ds_read_b128 v[114:117], v63 offset:12288
	v_mfma_f32_32x32x16_bf16 v[64:79], v[160:163], v[122:125], v[64:79]
	v_add_f32_e32 v118, v244, v243
	v_add_f32_e32 v119, v230, v251
	v_add_f32_e32 v118, v119, v118
	v_add_f32_e32 v113, v118, v113
	ds_read_b128 v[118:121], v63 offset:14336
	s_waitcnt vmcnt(0)
	s_add_i32 s9, s9, 1
	s_waitcnt lgkmcnt(0)
	v_mfma_f32_32x32x16_bf16 v[64:79], v[168:171], v[114:117], v[64:79]
	v_add_f32_e64 v114, v166, v164
	v_add_f32_e64 v115, v167, v165
	v_add_f32_e64 v116, v186, v184
	v_add_f32_e64 v117, v187, v185
	v_add_f32_e32 v209, v209, v113
	v_add_f32_e32 v114, v116, v114
	v_add_f32_e32 v115, v117, v115
	v_add_u32_e32 v212, 0x1000, v212
	v_pk_add_f32 v[114:115], v[114:115], v[114:115] op_sel:[0,1] op_sel_hi:[1,0]
	s_cmpk_eq_i32 s9, 0x83
	v_mfma_f32_32x32x16_bf16 v[64:79], v[176:179], v[118:121], v[64:79]
	v_add_f32_e64 v114, v127, v114
	v_add_f32_e64 v115, v126, v115
	v_add_u32_e32 v214, 64, v214
	s_waitcnt vmcnt(0)
	s_barrier
	s_cbranch_scc1 .LBB0_844
	s_mov_b32 s6, s10
	s_mov_b32 s10, s5
	s_mov_b32 s5, s11
	v_mov_b32_e32 v211, v114
	s_cmpk_gt_u32 s9, 0x80
	s_mov_b32 s11, s6
	s_cbranch_scc0 .LBB0_640
	s_branch .LBB0_644

.LBB0_774:
	v_add_u32_e32 v63, s14, v222
	v_mov_b32_e32 v113, 0
	v_mov_b32_e32 v126, 0
	v_add_u32_e32 v122, v63, v113
	ds_read_b128 v[114:117], v122
	ds_read_b128 v[122:125], v122 offset:512
	v_add3_u32 v113, v219, v113, s15
	ds_read_b128 v[118:121], v113
	v_add_u32_e32 v113, v63, v126
	ds_read_b128 v[226:229], v113 offset:2048
	s_waitcnt lgkmcnt(0)
	v_mfma_f32_32x32x16_bf16 v[176:191], v[114:117], v[118:121], v[80:95]
	ds_read_b128 v[238:241], v113 offset:2560
	v_add3_u32 v113, v219, v126, s18
	v_exp_f32_e32 v231, v98
	v_mfma_f32_32x32x16_bf16 v[160:175], v[122:125], v[118:121], v[80:95]
	ds_read_b128 v[116:119], v113
	v_mov_b32_e32 v98, 0
	v_exp_f32_e32 v234, v99
	v_exp_f32_e32 v122, v128
	v_add_u32_e32 v99, v63, v98
	v_add3_u32 v98, v219, v98, s19
	s_waitcnt lgkmcnt(0)
	v_mfma_f32_32x32x16_bf16 v[176:191], v[226:229], v[116:119], v[176:191]
	ds_read_b128 v[124:127], v99 offset:4096
	v_exp_f32_e32 v123, v129
	v_exp_f32_e32 v235, v130
	v_exp_f32_e32 v237, v131
	v_exp_f32_e32 v113, v100
	v_exp_f32_e32 v223, v101
	v_exp_f32_e32 v233, v102
	v_mfma_f32_32x32x16_bf16 v[160:175], v[238:241], v[116:119], v[160:175]
	ds_read_b128 v[116:119], v99 offset:4608
	ds_read_b128 v[128:131], v98
	v_mov_b32_e32 v99, 0
	v_exp_f32_e32 v238, v103
	v_add_u32_e32 v115, v63, v99
	v_add3_u32 v99, v219, v99, s22
	s_waitcnt lgkmcnt(0)
	v_mfma_f32_32x32x16_bf16 v[176:191], v[124:127], v[128:131], v[176:191]
	ds_read_b128 v[100:103], v115 offset:6144
	v_exp_f32_e32 v120, v96
	v_exp_f32_e32 v121, v97
	v_cvt_pk_bf16_f32 v97, v231, v234
	v_cvt_pk_bf16_f32 v98, v113, v223
	v_exp_f32_e32 v241, v104
	v_cvt_pk_bf16_f32 v96, v120, v121
	v_mfma_f32_32x32x16_bf16 v[160:175], v[116:119], v[128:131], v[160:175]
	ds_read_b128 v[116:119], v115 offset:6656
	ds_read_b128 v[124:127], v99
	v_cvt_pk_bf16_f32 v99, v233, v238
	v_exp_f32_e32 v242, v105
	v_exp_f32_e32 v249, v106
	v_exp_f32_e32 v250, v107
	v_exp_f32_e32 v246, v108
	s_waitcnt lgkmcnt(0)
	v_mfma_f32_32x32x16_bf16 v[176:191], v[100:103], v[124:127], v[176:191]
	v_exp_f32_e32 v248, v109
	v_exp_f32_e32 v243, v110
	v_exp_f32_e32 v244, v111
	v_cvt_pk_bf16_f32 v104, v241, v242
	v_cvt_pk_bf16_f32 v105, v249, v250
	v_cvt_pk_bf16_f32 v106, v246, v248
	v_cvt_pk_bf16_f32 v107, v243, v244
	v_mfma_f32_32x32x16_bf16 v[160:175], v[116:119], v[124:127], v[160:175]
	ds_read_b128 v[116:119], v63 offset:8192
	v_exp_f32_e32 v232, v132
	v_exp_f32_e32 v236, v133
	v_exp_f32_e32 v239, v134
	v_exp_f32_e32 v240, v135
	v_cvt_pk_bf16_f32 v114, v122, v123
	v_cvt_pk_bf16_f32 v115, v235, v237
	s_waitcnt lgkmcnt(0)
	v_mfma_f32_32x32x16_bf16 v[16:31], v[96:99], v[116:119], v[16:31]
	ds_read_b128 v[108:111], v63 offset:10240
	v_cvt_pk_bf16_f32 v116, v232, v236
	v_cvt_pk_bf16_f32 v117, v239, v240
	v_exp_f32_e32 v245, v136
	v_exp_f32_e32 v247, v137
	v_exp_f32_e32 v227, v138
	v_exp_f32_e32 v228, v139
	s_waitcnt lgkmcnt(0)
	v_mfma_f32_32x32x16_bf16 v[16:31], v[104:107], v[108:111], v[16:31]
	ds_read_b128 v[108:111], v63 offset:12288
	v_exp_f32_e32 v225, v140
	v_exp_f32_e32 v226, v141
	v_exp_f32_e32 v251, v142
	v_exp_f32_e32 v230, v143
	v_cvt_pk_bf16_f32 v128, v245, v247
	v_cvt_pk_bf16_f32 v129, v227, v228
	s_waitcnt lgkmcnt(0)
	v_mfma_f32_32x32x16_bf16 v[16:31], v[114:117], v[108:111], v[16:31]
	ds_read_b128 v[108:111], v63 offset:14336
	v_cvt_pk_bf16_f32 v130, v225, v226
	v_cvt_pk_bf16_f32 v131, v251, v230
	s_waitcnt lgkmcnt(0)
	s_nop 0
	v_mfma_f32_32x32x16_bf16 v[16:31], v[128:131], v[108:111], v[16:31]
	ds_read_b128 v[108:111], v63 offset:8704
	s_waitcnt lgkmcnt(0)
	v_mfma_f32_32x32x16_bf16 v[0:15], v[96:99], v[108:111], v[0:15]
	ds_read_b128 v[96:99], v63 offset:10752
	s_waitcnt lgkmcnt(0)
	v_mfma_f32_32x32x16_bf16 v[0:15], v[104:107], v[96:99], v[0:15]
	ds_read_b128 v[96:99], v63 offset:12800
	s_waitcnt lgkmcnt(0)
	v_mfma_f32_32x32x16_bf16 v[0:15], v[114:117], v[96:99], v[0:15]
	ds_read_b128 v[96:99], v63 offset:14848
	s_waitcnt lgkmcnt(0)
	v_mfma_f32_32x32x16_bf16 v[0:15], v[128:131], v[96:99], v[0:15]
	v_maximum3_f32 v96, v176, v160, v160
	v_maximum3_f32 v97, v161, v178, v162
	v_maximum3_f32 v96, v96, v177, v179
	v_maximum3_f32 v97, v97, v180, v164
	v_maximum3_f32 v96, v96, v163, v181
	v_maximum3_f32 v97, v97, v182, v166
	v_maximum3_f32 v96, v96, v165, v183
	v_maximum3_f32 v97, v97, v184, v168
	v_maximum3_f32 v96, v96, v167, v185
	v_maximum3_f32 v97, v97, v186, v170
	v_maximum3_f32 v96, v96, v169, v187
	v_maximum3_f32 v97, v97, v188, v172
	v_maximum3_f32 v96, v96, v171, v189
	v_maximum3_f32 v97, v97, v190, v174
	v_maximum3_f32 v96, v96, v173, v191
	v_maximum3_f32 v96, v96, v175, v97
	v_mov_b32_e32 v97, v96
	s_nop 1
	v_permlane32_swap_b32_e32 v96, v97
	v_maximum3_f32 v96, v96, v97, v97
	v_cmp_lt_f32_e32 vcc, s46, v96
	s_cbranch_vccz .LBB0_778
	v_max_f32_e32 v80, v96, v96
	v_max_f32_e32 v80, 0, v80
	v_exp_f32_e64 v81, -v80
	s_and_saveexec_b64 s[6:7], s[38:39]
	ds_write_b32 v209, v81 offset:49152
	s_or_b64 exec, exec, s[6:7]
	v_mul_f32_e32 v92, v212, v80
	v_mul_f32_e32 v93, v213, v81
	s_waitcnt lgkmcnt(0)
	v_sub_f32_e32 v176, v176, v80
	v_sub_f32_e32 v177, v177, v80
	v_add_u32_e32 v92, s67, v194
	v_sub_f32_e32 v160, v160, v80
	v_sub_f32_e32 v161, v161, v80
	v_sub_f32_e32 v178, v178, v80
	v_sub_f32_e32 v179, v179, v80
	v_sub_f32_e32 v162, v162, v80
	v_sub_f32_e32 v163, v163, v80
	v_sub_f32_e32 v180, v180, v80
	v_sub_f32_e32 v181, v181, v80
	v_sub_f32_e32 v164, v164, v80
	v_sub_f32_e32 v165, v165, v80
	v_sub_f32_e32 v182, v182, v80
	v_sub_f32_e32 v183, v183, v80
	v_sub_f32_e32 v166, v166, v80
	v_sub_f32_e32 v167, v167, v80
	v_sub_f32_e32 v184, v184, v80
	v_sub_f32_e32 v185, v185, v80
	v_sub_f32_e32 v168, v168, v80
	v_sub_f32_e32 v169, v169, v80
	v_sub_f32_e32 v186, v186, v80
	v_sub_f32_e32 v187, v187, v80
	v_sub_f32_e32 v170, v170, v80
	v_sub_f32_e32 v171, v171, v80
	v_sub_f32_e32 v188, v188, v80
	v_sub_f32_e32 v189, v189, v80
	v_sub_f32_e32 v172, v172, v80
	v_sub_f32_e32 v173, v173, v80
	v_sub_f32_e32 v190, v190, v80
	v_sub_f32_e32 v191, v191, v80
	v_sub_f32_e32 v174, v174, v80
	v_sub_f32_e32 v175, v175, v80
	v_add_f32_e32 v126, v212, v80
	v_add_f32_e32 v127, v213, v81
	ds_read_b128 v[80:83], v92 offset:49216
	ds_read_b128 v[84:87], v92 offset:49248
	ds_read_b128 v[88:91], v92 offset:49152
	ds_read_b128 v[96:99], v92 offset:49184
	v_mov_b32_e32 v127, v93
	s_waitcnt lgkmcnt(0)
	v_pk_add_f32 v[94:95], v[126:127], 0 neg_lo:[1,1] neg_hi:[1,1]
	s_waitcnt lgkmcnt(0)
	v_mul_f32_e32 v76, v76, v84
	v_mul_f32_e32 v77, v77, v85
	v_mul_f32_e32 v72, v72, v80
	v_mul_f32_e32 v73, v73, v81
	v_mul_f32_e32 v68, v68, v96
	v_mul_f32_e32 v69, v69, v97
	v_mul_f32_e32 v78, v78, v86
	v_mul_f32_e32 v79, v79, v87
	v_mul_f32_e32 v74, v74, v82
	v_mul_f32_e32 v75, v75, v83
	v_mul_f32_e32 v70, v70, v98
	v_mul_f32_e32 v71, v71, v99
	v_mul_f32_e32 v66, v66, v90
	v_mul_f32_e32 v67, v67, v91
	v_mul_f32_e32 v64, v64, v88
	v_mul_f32_e32 v65, v65, v89
	v_mul_f32_e32 v44, v44, v84
	v_mul_f32_e32 v45, v45, v85
	v_mul_f32_e32 v40, v40, v80
	v_mul_f32_e32 v41, v41, v81
	v_mul_f32_e32 v36, v36, v96
	v_mul_f32_e32 v37, v37, v97
	v_mul_f32_e32 v46, v46, v86
	v_mul_f32_e32 v47, v47, v87
	v_mul_f32_e32 v42, v42, v82
	v_mul_f32_e32 v43, v43, v83
	v_mul_f32_e32 v38, v38, v98
	v_mul_f32_e32 v39, v39, v99
	v_mul_f32_e32 v34, v34, v90
	v_mul_f32_e32 v35, v35, v91
	v_mul_f32_e32 v32, v32, v88
	v_mul_f32_e32 v33, v33, v89
	v_mov_b32_e32 v212, v126
	v_mov_b32_e32 v95, v94
	v_mov_b32_e32 v93, v94
	v_mov_b32_e32 v92, v94
	v_mov_b32_e32 v91, v94
	v_mov_b32_e32 v90, v94
	v_mov_b32_e32 v89, v94
	v_mov_b32_e32 v88, v94
	v_mov_b32_e32 v87, v94
	v_mov_b32_e32 v86, v94
	v_mov_b32_e32 v85, v94
	v_mov_b32_e32 v84, v94
	v_mov_b32_e32 v83, v94
	v_mov_b32_e32 v82, v94
	v_mov_b32_e32 v81, v94
	v_mov_b32_e32 v80, v94
	s_branch .LBB0_779

.LBB0_779:
	v_add_u32_e32 v213, s11, v222
	v_mov_b32_e32 v96, 0
	v_mov_b32_e32 v124, 0
	v_add_u32_e32 v97, v213, v96
	ds_read_b128 v[114:117], v97
	ds_read_b128 v[132:135], v97 offset:512
	v_add_u32_e32 v96, v219, v96
	ds_read_b128 v[128:131], v96 offset:51200
	v_exp_f32_e32 v125, v176
	v_add_u32_e32 v118, v213, v124
	ds_read_b128 v[136:139], v118 offset:2048
	s_waitcnt lgkmcnt(0)
	v_mfma_f32_32x32x16_bf16 v[96:111], v[114:117], v[128:131], v[144:159]
	ds_read_b128 v[116:119], v118 offset:2560
	v_add_u32_e32 v114, v219, v124
	v_exp_f32_e32 v124, v178
	v_add_f32_e32 v140, v121, v120
	v_add_f32_e32 v141, v123, v122
	v_exp_f32_e32 v229, v166
	v_exp_f32_e32 v224, v167
	v_mfma_f32_32x32x16_bf16 v[144:159], v[132:135], v[128:131], v[144:159]
	v_exp_f32_e32 v133, v177
	v_exp_f32_e32 v129, v160
	v_exp_f32_e32 v131, v161
	v_exp_f32_e32 v132, v179
	v_exp_f32_e32 v128, v162
	v_exp_f32_e32 v130, v163
	ds_read_b128 v[120:123], v114 offset:59392
	v_add_f32_e32 v134, v132, v124
	v_add_f32_e32 v135, v133, v125
	s_waitcnt lgkmcnt(0)
	v_mfma_f32_32x32x16_bf16 v[96:111], v[136:139], v[120:123], v[96:111]
	v_add_f32_e64 v142, v130, v128
	v_add_f32_e64 v143, v131, v129
	v_mov_b32_e32 v136, 0
	v_add_f32_e64 v134, v142, v134
	v_add_f32_e64 v135, v143, v135
	v_cvt_pk_bf16_f32 v114, v125, v133
	v_add_f32_e32 v115, 0, v135
	v_add_f32_e32 v143, v134, v115
	v_cvt_pk_bf16_f32 v115, v124, v132
	v_exp_f32_e32 v133, v180
	v_add_u32_e32 v124, v213, v136
	v_exp_f32_e32 v135, v181
	v_exp_f32_e32 v132, v164
	v_exp_f32_e32 v134, v165
	ds_read_b128 v[160:163], v124 offset:4096
	v_mfma_f32_32x32x16_bf16 v[144:159], v[116:119], v[120:123], v[144:159]
	ds_read_b128 v[122:125], v124 offset:4608
	v_add3_u32 v116, v219, v136, s45
	ds_read_b128 v[176:179], v116
	v_add_f32_e64 v116, v134, v132
	v_add_f32_e64 v117, v135, v133
	v_exp_f32_e32 v118, v182
	v_exp_f32_e32 v119, v183
	v_add_f32_e32 v166, v116, v116
	v_add_f32_e32 v167, v116, v117
	v_exp_f32_e32 v142, v184
	v_exp_f32_e32 v166, v185
	v_exp_f32_e32 v136, v168
	v_exp_f32_e32 v138, v169
	v_mov_b32_e32 v200, 0
	v_exp_f32_e32 v181, v186
	v_exp_f32_e32 v183, v187
	v_exp_f32_e32 v180, v170
	v_exp_f32_e32 v182, v171
	v_cvt_pk_bf16_f32 v116, v133, v135
	v_add_f32_e32 v137, v119, v118
	v_add_f32_e32 v139, v224, v229
	v_cvt_pk_bf16_f32 v117, v118, v119
	v_add_u32_e32 v133, v213, v200
	s_waitcnt lgkmcnt(0)
	v_mfma_f32_32x32x16_bf16 v[96:111], v[160:163], v[176:179], v[96:111]
	ds_read_b128 v[118:121], v133 offset:6144
	v_add_f32_e64 v160, v166, v142
	v_add_f32_e64 v161, v167, v143
	v_add_f32_e64 v162, v138, v136
	v_add_f32_e64 v163, v139, v137
	v_exp_f32_e32 v185, v188
	v_add_f32_e32 v160, v162, v160
	v_add_f32_e32 v161, v163, v161
	v_exp_f32_e32 v187, v189
	v_add_f32_e32 v164, v160, v160
	v_add_f32_e32 v165, v160, v161
	v_mfma_f32_32x32x16_bf16 v[144:159], v[122:125], v[176:179], v[144:159]
	ds_read_b128 v[122:125], v133 offset:6656
	ds_read_b128 v[168:171], v63 offset:8704
	v_cvt_pk_bf16_f32 v160, v142, v166
	v_add_f32_e64 v142, v182, v180
	v_add_f32_e64 v143, v183, v181
	v_exp_f32_e32 v164, v190
	v_add_f32_e32 v166, v142, v142
	v_add_f32_e32 v167, v142, v143
	v_exp_f32_e32 v166, v191
	s_waitcnt lgkmcnt(0)
	v_mfma_f32_32x32x16_bf16 v[32:47], v[114:117], v[168:171], v[32:47]
	ds_read_b128 v[176:179], v63 offset:10752
	v_cvt_pk_bf16_f32 v161, v181, v183
	v_cvt_pk_bf16_f32 v162, v185, v187
	v_cvt_pk_bf16_f32 v163, v164, v166
	v_cvt_pk_bf16_f32 v168, v129, v131
	v_cvt_pk_bf16_f32 v169, v128, v130
	v_cvt_pk_bf16_f32 v170, v132, v134
	s_waitcnt lgkmcnt(0)
	v_mfma_f32_32x32x16_bf16 v[32:47], v[160:163], v[176:179], v[32:47]
	ds_read_b128 v[128:131], v63 offset:12800
	v_cvt_pk_bf16_f32 v171, v229, v224
	v_exp_f32_e32 v181, v172
	v_exp_f32_e32 v183, v173
	v_exp_f32_e32 v184, v174
	v_exp_f32_e32 v186, v175
	v_cvt_pk_bf16_f32 v176, v136, v138
	s_waitcnt lgkmcnt(0)
	v_mfma_f32_32x32x16_bf16 v[32:47], v[168:171], v[128:131], v[32:47]
	ds_read_b128 v[132:135], v63 offset:14848
	v_cvt_pk_bf16_f32 v177, v180, v182
	v_cvt_pk_bf16_f32 v178, v181, v183
	v_cvt_pk_bf16_f32 v179, v184, v186
	v_add_f32_e32 v129, v234, v231
	v_add_f32_e32 v130, v237, v235
	v_add_f32_e32 v129, v130, v129
	v_add3_u32 v130, v219, v200, s58
	s_waitcnt lgkmcnt(0)
	v_mfma_f32_32x32x16_bf16 v[32:47], v[176:179], v[132:135], v[32:47]
	ds_read_b128 v[172:175], v130
	v_add_f32_e32 v128, v141, v140
	v_add_f32_e32 v128, 0, v128
	v_add_f32_e32 v128, v129, v128
	v_add_f32_e32 v113, v223, v113
	v_add_f32_e32 v129, v236, v232
	v_add_f32_e32 v113, v129, v113
	s_waitcnt lgkmcnt(0)
	v_mfma_f32_32x32x16_bf16 v[96:111], v[118:121], v[172:175], v[96:111]
	v_add_f32_e32 v118, v238, v233
	v_add_f32_e32 v119, v240, v239
	v_add_f32_e32 v113, v113, v128
	v_add_f32_e32 v118, v119, v118
	v_add_f32_e32 v113, v118, v113
	ds_read_b128 v[118:121], v63 offset:8192
	v_mfma_f32_32x32x16_bf16 v[128:143], v[122:125], v[172:175], v[144:159]
	v_add_f32_e32 v122, v242, v241
	v_add_f32_e32 v123, v247, v245
	v_add_f32_e32 v122, v123, v122
	v_add_f32_e32 v113, v122, v113
	ds_read_b128 v[122:125], v63 offset:10240
	v_add_f32_e32 v185, v187, v185
	v_add_f32_e32 v187, v183, v181
	s_waitcnt lgkmcnt(0)
	v_mfma_f32_32x32x16_bf16 v[64:79], v[114:117], v[118:121], v[64:79]
	v_add_f32_e32 v144, v250, v249
	v_add_f32_e32 v145, v228, v227
	v_add_f32_e32 v114, v145, v144
	v_add_f32_e32 v113, v114, v113
	v_add_f32_e32 v114, v248, v246
	v_add_f32_e32 v115, v226, v225
	v_add_f32_e32 v114, v115, v114
	v_add_f32_e32 v113, v114, v113
	ds_read_b128 v[114:117], v63 offset:12288
	v_mfma_f32_32x32x16_bf16 v[64:79], v[160:163], v[122:125], v[64:79]
	v_add_f32_e32 v118, v244, v243
	v_add_f32_e32 v119, v230, v251
	v_add_f32_e32 v118, v119, v118
	v_add_f32_e32 v113, v118, v113
	ds_read_b128 v[118:121], v63 offset:14336
	s_waitcnt vmcnt(0)
	s_add_i32 s13, s13, 1
	s_waitcnt lgkmcnt(0)
	v_mfma_f32_32x32x16_bf16 v[64:79], v[168:171], v[114:117], v[64:79]
	v_add_f32_e64 v114, v166, v164
	v_add_f32_e64 v115, v167, v165
	v_add_f32_e64 v116, v186, v184
	v_add_f32_e64 v117, v187, v185
	s_add_i32 s12, s12, 64
	v_add_f32_e32 v114, v116, v114
	v_add_f32_e32 v115, v117, v115
	v_add_f32_e32 v211, v211, v113
	v_pk_add_f32 v[114:115], v[114:115], v[114:115] op_sel:[0,1] op_sel_hi:[1,0]
	s_cmpk_eq_i32 s13, 0x83
	v_mfma_f32_32x32x16_bf16 v[64:79], v[176:179], v[118:121], v[64:79]
	v_add_f32_e64 v114, v127, v114
	v_add_f32_e64 v115, v126, v115
	s_waitcnt vmcnt(0)
	s_barrier
	s_cbranch_scc1 .LBB0_831
	s_mov_b32 s6, s11
	s_mov_b32 s11, s9
	s_mov_b32 s9, s14
	v_mov_b32_e32 v213, v114
	s_cmpk_gt_u32 s13, 0x80
	s_mov_b32 s14, s6
	s_cbranch_scc0 .LBB0_765
	s_branch .LBB0_769
